# GEMM loop: static priority form plus the 12 duplicate s_waitcnt lgkmcnt(0) in front of the MFMA blocks removed (the template wait directly above already covers them)
# speedup vs baseline: 1.0160x; 1.0160x over previous
; #define PG8_STAGE(bufoff, gbase, voff) do { _Pragma("unroll") for (int _i = 0; _i < 2; ++_i) \
;         __builtin_amdgcn_global_load_lds((const unsigned*)((const char*)(gbase) + (voff)[_i]), (LAS unsigned*)(lds + (bufoff) + ldsw + _i * 8192), 16, 0, 0); } while (0)
; #define PG8_LDA(dst, b, h) do { _Pragma("unroll") for (int m = 0; m < 4; ++m) _Pragma("unroll") for (int k = 0; k < 2; ++k) dst[m][k] = *(const LAS bf16x8*)(lds + PG8_SA(b, h) + aoff + m * 2048 + k * 1024); } while (0)
; #define PG8_LDB(dst, b, h) do { _Pragma("unroll") for (int n = 0; n < 2; ++n) _Pragma("unroll") for (int k = 0; k < 2; ++k) dst[n][k] = *(const LAS bf16x8*)(lds + PG8_SB(b, h) + boff + n * 2048 + k * 1024); } while (0)
; #define PG8_MMA(ai, bj, At, Bt) do { __builtin_amdgcn_s_setprio(1); _Pragma("unroll") for (int m = 0; m < 4; ++m) _Pragma("unroll") for (int n = 0; n < 2; ++n) _Pragma("unroll") for (int k = 0; k < 2; ++k) \
;         acc[ai][bj][m][n] = __builtin_amdgcn_mfma_f32_16x16x32_bf16(Bt[n][k], At[m][k], acc[ai][bj][m][n], 0, 0, 0); __builtin_amdgcn_s_setprio(0); } while (0)
; #define PG8_WAIT_V(n) asm volatile("s_waitcnt vmcnt(" #n ")" ::: "memory")
; #define PG8_WAIT_L(n) asm volatile("s_waitcnt lgkmcnt(" #n ")" ::: "memory")
; #define PG8_BAR __builtin_amdgcn_s_barrier()
; __device__ __forceinline__ void gemm_phase(LAS unsigned char* lds, const Params& p, const Sched& S, float alpha, const int TIDX) {
;     ...
;         for (int t = 0; t < nt; t += 2) {
;             const bool last = (t == nt - 2);
;             const char* a1 = cA + (size_t)(t + 1) * kstep;
;             const char* a2 = last ? nA : cA + (size_t)(t + 2) * kstep; const char* b2 = last ? nB : cB + (size_t)(t + 2) * kstep;
;             const char* a3 = a2 + kstep; const char* b3 = b2 + kstep;
;             PG8_LDB(B0, 0, 0); PG8_SCHED; PG8_LDA(At, 0, 0); PG8_STAGE(PG8_SA(1, 1), a1 + hstep, voffA);
;             PG8_WAIT_L(8); PG8_BAR; PG8_WAIT_L(0); PG8_MMA(0, 0, At, B0); PG8_BAR; PG8_SCHED;
;             PG8_LDB(B1, 0, 1); PG8_STAGE(PG8_SB(0, 0), b2, voffB);
;             PG8_BAR; PG8_WAIT_L(0); PG8_MMA(0, 1, At, B1); PG8_BAR;
;             PG8_LDA(At, 0, 1); PG8_STAGE(PG8_SA(0, 0), a2, voffA);
;             PG8_BAR; PG8_WAIT_L(0); PG8_MMA(1, 0, At, B0); PG8_BAR; PG8_SCHED;
;             PG8_STAGE(PG8_SB(0, 1), b2 + hstep, voffB);
;             PG8_WAIT_V(6); PG8_BAR; PG8_MMA(1, 1, At, B1); PG8_BAR;
.Lgemm_prio_done:
	s_add_i32 s57, s48, 2
	s_add_u32 s50, s6, 0x80
	s_addc_u32 s49, s7, 0
	s_add_i32 s74, 0, 0x10000
	v_add_u32_e32 v0, s74, v200
	ds_read_b128 v[130:133], v0
	ds_read_b128 v[134:137], v0 offset:1024
	ds_read_b128 v[154:157], v0 offset:2048
	ds_read_b128 v[158:161], v0 offset:3072
	s_cmp_eq_u32 s38, s48
	s_cselect_b32 s48, s44, s50
	s_cselect_b32 s49, s45, s49
	s_cselect_b32 s51, s47, s56
	s_cselect_b32 s50, s46, s39
	v_lshl_add_u64 v[166:167], s[6:7], 0, v[150:151]
	s_add_i32 m0, s35, 0xc000
	ds_read_b128 v[162:165], v202
	ds_read_b128 v[170:173], v202 offset:1024
	ds_read_b128 v[174:177], v202 offset:2048
	ds_read_b128 v[178:181], v202 offset:3072
	ds_read_b128 v[182:185], v202 offset:4096
	ds_read_b128 v[204:207], v202 offset:5120
	ds_read_b128 v[208:211], v202 offset:6144
	ds_read_b128 v[212:215], v202 offset:7168
	global_load_lds_dwordx4 v[166:167], off
	v_lshl_add_u64 v[166:167], s[6:7], 0, v[152:153]
	s_add_i32 m0, s35, 0xe000
	s_nop 0
	global_load_lds_dwordx4 v[166:167], off
	s_waitcnt lgkmcnt(8)
	s_barrier
	s_waitcnt lgkmcnt(0)
	v_mfma_f32_16x16x32_bf16 v[126:129], v[130:133], v[162:165], 0
	v_mfma_f32_16x16x32_bf16 v[118:121], v[154:157], v[162:165], 0
	v_mfma_f32_16x16x32_bf16 v[110:113], v[130:133], v[174:177], 0
	v_mfma_f32_16x16x32_bf16 v[102:105], v[154:157], v[174:177], 0
	v_mfma_f32_16x16x32_bf16 v[94:97], v[130:133], v[182:185], 0
	v_mfma_f32_16x16x32_bf16 v[86:89], v[154:157], v[182:185], 0
	v_mfma_f32_16x16x32_bf16 v[78:81], v[130:133], v[208:211], 0
	v_mfma_f32_16x16x32_bf16 v[70:73], v[154:157], v[208:211], 0
	v_mfma_f32_16x16x32_bf16 v[126:129], v[134:137], v[170:173], v[126:129]
	v_mfma_f32_16x16x32_bf16 v[118:121], v[158:161], v[170:173], v[118:121]
	v_mfma_f32_16x16x32_bf16 v[110:113], v[134:137], v[178:181], v[110:113]
	v_mfma_f32_16x16x32_bf16 v[102:105], v[158:161], v[178:181], v[102:105]
	v_mfma_f32_16x16x32_bf16 v[94:97], v[134:137], v[204:207], v[94:97]
	v_mfma_f32_16x16x32_bf16 v[86:89], v[158:161], v[204:207], v[86:89]
	v_mfma_f32_16x16x32_bf16 v[78:81], v[134:137], v[212:215], v[78:81]
	v_mfma_f32_16x16x32_bf16 v[70:73], v[158:161], v[212:215], v[70:73]
	s_barrier
	s_add_i32 s75, 0, 0x14000
	s_add_i32 s74, s74, s34
	v_add_u32_e32 v0, s75, v200
	v_lshl_add_u64 v[166:167], s[50:51], 0, v[140:141]
	s_mov_b32 m0, s74
	ds_read_b128 v[216:219], v0
	ds_read_b128 v[220:223], v0 offset:1024
	ds_read_b128 v[224:227], v0 offset:2048
	ds_read_b128 v[228:231], v0 offset:3072
	global_load_lds_dwordx4 v[166:167], off
	v_lshl_add_u64 v[186:187], s[50:51], 0, v[144:145]
	s_add_i32 m0, s74, 0x2000
	s_nop 0
	global_load_lds_dwordx4 v[186:187], off
	s_barrier
	s_waitcnt lgkmcnt(0)
	v_mfma_f32_16x16x32_bf16 v[122:125], v[216:219], v[162:165], 0
	v_mfma_f32_16x16x32_bf16 v[114:117], v[224:227], v[162:165], 0
	v_mfma_f32_16x16x32_bf16 v[106:109], v[216:219], v[174:177], 0
	v_mfma_f32_16x16x32_bf16 v[98:101], v[224:227], v[174:177], 0
	v_mfma_f32_16x16x32_bf16 v[90:93], v[216:219], v[182:185], 0
	v_mfma_f32_16x16x32_bf16 v[82:85], v[224:227], v[182:185], 0
	v_mfma_f32_16x16x32_bf16 v[74:77], v[216:219], v[208:211], 0
	v_mfma_f32_16x16x32_bf16 v[66:69], v[224:227], v[208:211], 0
	v_mfma_f32_16x16x32_bf16 v[122:125], v[220:223], v[170:173], v[122:125]
	v_mfma_f32_16x16x32_bf16 v[114:117], v[228:231], v[170:173], v[114:117]
	v_mfma_f32_16x16x32_bf16 v[106:109], v[220:223], v[178:181], v[106:109]
	v_mfma_f32_16x16x32_bf16 v[98:101], v[228:231], v[178:181], v[98:101]
	v_mfma_f32_16x16x32_bf16 v[90:93], v[220:223], v[204:207], v[90:93]
	v_mfma_f32_16x16x32_bf16 v[82:85], v[228:231], v[204:207], v[82:85]
	v_mfma_f32_16x16x32_bf16 v[74:77], v[220:223], v[212:215], v[74:77]
	v_mfma_f32_16x16x32_bf16 v[66:69], v[228:231], v[212:215], v[66:69]
	s_mov_b32 m0, s35
	v_lshl_add_u64 v[232:233], s[48:49], 0, v[138:139]
	s_barrier
	ds_read_b128 v[162:165], v202 offset:16384
	ds_read_b128 v[170:173], v202 offset:17408
	ds_read_b128 v[174:177], v202 offset:18432
	ds_read_b128 v[178:181], v202 offset:19456
	ds_read_b128 v[182:185], v202 offset:20480
	ds_read_b128 v[204:207], v202 offset:21504
	ds_read_b128 v[208:211], v202 offset:22528
	ds_read_b128 v[212:215], v202 offset:23552
	global_load_lds_dwordx4 v[232:233], off
	v_lshl_add_u64 v[234:235], s[48:49], 0, v[142:143]
	s_mov_b32 m0, s36
	s_nop 0
	global_load_lds_dwordx4 v[234:235], off
	s_barrier
	s_waitcnt lgkmcnt(0)
	v_mfma_f32_16x16x32_bf16 v[62:65], v[130:133], v[162:165], 0
	v_mfma_f32_16x16x32_bf16 v[54:57], v[154:157], v[162:165], 0
	v_mfma_f32_16x16x32_bf16 v[46:49], v[130:133], v[174:177], 0
	v_mfma_f32_16x16x32_bf16 v[38:41], v[154:157], v[174:177], 0
	v_mfma_f32_16x16x32_bf16 v[30:33], v[130:133], v[182:185], 0
	v_mfma_f32_16x16x32_bf16 v[22:25], v[154:157], v[182:185], 0
	v_mfma_f32_16x16x32_bf16 v[14:17], v[130:133], v[208:211], 0
	v_mfma_f32_16x16x32_bf16 v[6:9], v[154:157], v[208:211], 0
	v_mfma_f32_16x16x32_bf16 v[62:65], v[134:137], v[170:173], v[62:65]
	v_mfma_f32_16x16x32_bf16 v[54:57], v[158:161], v[170:173], v[54:57]
	v_mfma_f32_16x16x32_bf16 v[46:49], v[134:137], v[178:181], v[46:49]
	v_mfma_f32_16x16x32_bf16 v[38:41], v[158:161], v[178:181], v[38:41]
	v_mfma_f32_16x16x32_bf16 v[30:33], v[134:137], v[204:207], v[30:33]
	v_mfma_f32_16x16x32_bf16 v[22:25], v[158:161], v[204:207], v[22:25]
	v_mfma_f32_16x16x32_bf16 v[14:17], v[134:137], v[212:215], v[14:17]
	v_mfma_f32_16x16x32_bf16 v[6:9], v[158:161], v[212:215], v[6:9]
	s_barrier
	s_add_u32 s50, s50, s20
	s_addc_u32 s51, s51, 0
	s_add_i32 s74, s75, s34
	v_lshl_add_u64 v[236:237], s[50:51], 0, v[140:141]
	s_mov_b32 m0, s74
	v_lshl_add_u64 v[238:239], s[50:51], 0, v[144:145]
	global_load_lds_dwordx4 v[236:237], off
	s_add_i32 m0, s74, 0x2000
	s_nop 0
	global_load_lds_dwordx4 v[238:239], off
	s_waitcnt vmcnt(6)
	s_barrier
; #define PG8_STAGE(bufoff, gbase, voff) do { _Pragma("unroll") for (int _i = 0; _i < 2; ++_i) \
;         __builtin_amdgcn_global_load_lds((const unsigned*)((const char*)(gbase) + (voff)[_i]), (LAS unsigned*)(lds + (bufoff) + ldsw + _i * 8192), 16, 0, 0); } while (0)
; #define PG8_LDA(dst, b, h) do { _Pragma("unroll") for (int m = 0; m < 4; ++m) _Pragma("unroll") for (int k = 0; k < 2; ++k) dst[m][k] = *(const LAS bf16x8*)(lds + PG8_SA(b, h) + aoff + m * 2048 + k * 1024); } while (0)
; #define PG8_LDB(dst, b, h) do { _Pragma("unroll") for (int n = 0; n < 2; ++n) _Pragma("unroll") for (int k = 0; k < 2; ++k) dst[n][k] = *(const LAS bf16x8*)(lds + PG8_SB(b, h) + boff + n * 2048 + k * 1024); } while (0)
; #define PG8_MMA(ai, bj, At, Bt) do { __builtin_amdgcn_s_setprio(1); _Pragma("unroll") for (int m = 0; m < 4; ++m) _Pragma("unroll") for (int n = 0; n < 2; ++n) _Pragma("unroll") for (int k = 0; k < 2; ++k) \
;         acc[ai][bj][m][n] = __builtin_amdgcn_mfma_f32_16x16x32_bf16(Bt[n][k], At[m][k], acc[ai][bj][m][n], 0, 0, 0); __builtin_amdgcn_s_setprio(0); } while (0)
; #define PG8_WAIT_V(n) asm volatile("s_waitcnt vmcnt(" #n ")" ::: "memory")
; #define PG8_WAIT_L(n) asm volatile("s_waitcnt lgkmcnt(" #n ")" ::: "memory")
; #define PG8_BAR __builtin_amdgcn_s_barrier()
; #define PG8_SCHED __builtin_amdgcn_sched_barrier(0)
; __device__ __forceinline__ void gemm_phase(LAS unsigned char* lds, const Params& p, const Sched& S, float alpha, const int TIDX) {
;     ...
;             PG8_WAIT_V(6); PG8_BAR; PG8_MMA(1, 1, At, B1); PG8_BAR;
;             PG8_LDB(B0, 1, 0); PG8_SCHED; PG8_LDA(At, 1, 0); PG8_STAGE(PG8_SA(0, 1), a2 + hstep, voffA);
;             PG8_WAIT_L(8); PG8_BAR; PG8_WAIT_L(0); PG8_MMA(0, 0, At, B0); PG8_BAR; PG8_SCHED;
;             PG8_LDB(B1, 1, 1); PG8_STAGE(PG8_SB(1, 0), b3, voffB);
;             PG8_BAR; PG8_WAIT_L(0); PG8_MMA(0, 1, At, B1); PG8_BAR;
;             PG8_LDA(At, 1, 1); PG8_STAGE(PG8_SA(1, 0), a3, voffA);
;             PG8_BAR; PG8_WAIT_L(0); PG8_MMA(1, 0, At, B0); PG8_BAR; PG8_SCHED;
	v_mfma_f32_16x16x32_bf16 v[58:61], v[216:219], v[162:165], 0
	v_mfma_f32_16x16x32_bf16 v[50:53], v[224:227], v[162:165], 0
	v_mfma_f32_16x16x32_bf16 v[42:45], v[216:219], v[174:177], 0
	v_mfma_f32_16x16x32_bf16 v[34:37], v[224:227], v[174:177], 0
	v_mfma_f32_16x16x32_bf16 v[26:29], v[216:219], v[182:185], 0
	v_mfma_f32_16x16x32_bf16 v[18:21], v[224:227], v[182:185], 0
	v_mfma_f32_16x16x32_bf16 v[10:13], v[216:219], v[208:211], 0
	v_mfma_f32_16x16x32_bf16 v[2:5], v[224:227], v[208:211], 0
	v_mfma_f32_16x16x32_bf16 v[58:61], v[220:223], v[170:173], v[58:61]
	v_mfma_f32_16x16x32_bf16 v[50:53], v[228:231], v[170:173], v[50:53]
	v_mfma_f32_16x16x32_bf16 v[42:45], v[220:223], v[178:181], v[42:45]
	v_mfma_f32_16x16x32_bf16 v[34:37], v[228:231], v[178:181], v[34:37]
	v_mfma_f32_16x16x32_bf16 v[26:29], v[220:223], v[204:207], v[26:29]
	v_mfma_f32_16x16x32_bf16 v[18:21], v[228:231], v[204:207], v[18:21]
	v_mfma_f32_16x16x32_bf16 v[10:13], v[220:223], v[212:215], v[10:13]
	v_mfma_f32_16x16x32_bf16 v[2:5], v[228:231], v[212:215], v[2:5]
	s_add_i32 s50, 0, 0x18000
	v_add_u32_e32 v0, s50, v200
	s_barrier
	ds_read_b128 v[130:133], v0
	ds_read_b128 v[134:137], v0 offset:1024
	ds_read_b128 v[154:157], v0 offset:2048
	ds_read_b128 v[158:161], v0 offset:3072
	s_add_u32 s48, s48, s20
	s_addc_u32 s49, s49, 0
	s_mov_b32 m0, s37
	v_lshl_add_u64 v[216:217], s[48:49], 0, v[138:139]
	ds_read_b128 v[162:165], v202 offset:32768
	ds_read_b128 v[170:173], v202 offset:33792
	ds_read_b128 v[174:177], v202 offset:34816
	ds_read_b128 v[178:181], v202 offset:35840
	ds_read_b128 v[182:185], v202 offset:36864
	ds_read_b128 v[204:207], v202 offset:37888
	ds_read_b128 v[208:211], v202 offset:38912
	ds_read_b128 v[212:215], v202 offset:39936
	global_load_lds_dwordx4 v[216:217], off
	v_lshl_add_u64 v[216:217], s[48:49], 0, v[142:143]
	s_mov_b32 m0, s24
	s_nop 0
	global_load_lds_dwordx4 v[216:217], off
	s_waitcnt lgkmcnt(8)
	s_barrier
	s_waitcnt lgkmcnt(0)
	v_mfma_f32_16x16x32_bf16 v[126:129], v[130:133], v[162:165], v[126:129]
	v_mfma_f32_16x16x32_bf16 v[118:121], v[154:157], v[162:165], v[118:121]
	v_mfma_f32_16x16x32_bf16 v[110:113], v[130:133], v[174:177], v[110:113]
	v_mfma_f32_16x16x32_bf16 v[102:105], v[154:157], v[174:177], v[102:105]
	v_mfma_f32_16x16x32_bf16 v[94:97], v[130:133], v[182:185], v[94:97]
	v_mfma_f32_16x16x32_bf16 v[86:89], v[154:157], v[182:185], v[86:89]
	v_mfma_f32_16x16x32_bf16 v[78:81], v[130:133], v[208:211], v[78:81]
	v_mfma_f32_16x16x32_bf16 v[70:73], v[154:157], v[208:211], v[70:73]
	v_mfma_f32_16x16x32_bf16 v[126:129], v[134:137], v[170:173], v[126:129]
	v_mfma_f32_16x16x32_bf16 v[118:121], v[158:161], v[170:173], v[118:121]
	v_mfma_f32_16x16x32_bf16 v[110:113], v[134:137], v[178:181], v[110:113]
	v_mfma_f32_16x16x32_bf16 v[102:105], v[158:161], v[178:181], v[102:105]
	v_mfma_f32_16x16x32_bf16 v[94:97], v[134:137], v[204:207], v[94:97]
	v_mfma_f32_16x16x32_bf16 v[86:89], v[158:161], v[204:207], v[86:89]
	v_mfma_f32_16x16x32_bf16 v[78:81], v[134:137], v[212:215], v[78:81]
	v_mfma_f32_16x16x32_bf16 v[70:73], v[158:161], v[212:215], v[70:73]
	s_barrier
	s_add_i32 s48, 0, 0x1c000
	s_add_i32 s49, s50, s34
	v_add_u32_e32 v0, s48, v200
	v_lshl_add_u64 v[166:167], v[166:167], 0, s[88:89]
	s_mov_b32 m0, s49
	ds_read_b128 v[216:219], v0
	ds_read_b128 v[220:223], v0 offset:1024
	ds_read_b128 v[224:227], v0 offset:2048
	ds_read_b128 v[228:231], v0 offset:3072
	global_load_lds_dwordx4 v[166:167], off
	v_lshl_add_u64 v[166:167], v[186:187], 0, s[88:89]
	s_add_i32 m0, s49, 0x2000
	s_nop 0
	global_load_lds_dwordx4 v[166:167], off
	s_barrier
	s_waitcnt lgkmcnt(0)
	v_mfma_f32_16x16x32_bf16 v[122:125], v[216:219], v[162:165], v[122:125]
	v_mfma_f32_16x16x32_bf16 v[114:117], v[224:227], v[162:165], v[114:117]
	v_mfma_f32_16x16x32_bf16 v[106:109], v[216:219], v[174:177], v[106:109]
	v_mfma_f32_16x16x32_bf16 v[98:101], v[224:227], v[174:177], v[98:101]
	v_mfma_f32_16x16x32_bf16 v[90:93], v[216:219], v[182:185], v[90:93]
	v_mfma_f32_16x16x32_bf16 v[82:85], v[224:227], v[182:185], v[82:85]
	v_mfma_f32_16x16x32_bf16 v[74:77], v[216:219], v[208:211], v[74:77]
	v_mfma_f32_16x16x32_bf16 v[66:69], v[224:227], v[208:211], v[66:69]
	v_mfma_f32_16x16x32_bf16 v[122:125], v[220:223], v[170:173], v[122:125]
	v_mfma_f32_16x16x32_bf16 v[114:117], v[228:231], v[170:173], v[114:117]
	v_mfma_f32_16x16x32_bf16 v[106:109], v[220:223], v[178:181], v[106:109]
	v_mfma_f32_16x16x32_bf16 v[98:101], v[228:231], v[178:181], v[98:101]
	v_mfma_f32_16x16x32_bf16 v[90:93], v[220:223], v[204:207], v[90:93]
	v_mfma_f32_16x16x32_bf16 v[82:85], v[228:231], v[204:207], v[82:85]
	v_mfma_f32_16x16x32_bf16 v[74:77], v[220:223], v[212:215], v[74:77]
	v_mfma_f32_16x16x32_bf16 v[66:69], v[228:231], v[212:215], v[66:69]
	s_mov_b32 m0, s25
	v_lshl_add_u64 v[166:167], v[232:233], 0, s[88:89]
	s_barrier
	ds_read_b128 v[162:165], v202 offset:49152
	ds_read_b128 v[170:173], v202 offset:50176
	ds_read_b128 v[174:177], v202 offset:51200
	ds_read_b128 v[178:181], v202 offset:52224
	ds_read_b128 v[182:185], v202 offset:53248
	ds_read_b128 v[204:207], v202 offset:54272
	ds_read_b128 v[208:211], v202 offset:55296
	ds_read_b128 v[212:215], v202 offset:56320
	global_load_lds_dwordx4 v[166:167], off
	v_lshl_add_u64 v[166:167], v[234:235], 0, s[88:89]
	s_mov_b32 m0, s68
	s_nop 0
	global_load_lds_dwordx4 v[166:167], off
	s_barrier
; #define PG8_STAGE(bufoff, gbase, voff) do { _Pragma("unroll") for (int _i = 0; _i < 2; ++_i) \
;         __builtin_amdgcn_global_load_lds((const unsigned*)((const char*)(gbase) + (voff)[_i]), (LAS unsigned*)(lds + (bufoff) + ldsw + _i * 8192), 16, 0, 0); } while (0)
; #define PG8_LDA(dst, b, h) do { _Pragma("unroll") for (int m = 0; m < 4; ++m) _Pragma("unroll") for (int k = 0; k < 2; ++k) dst[m][k] = *(const LAS bf16x8*)(lds + PG8_SA(b, h) + aoff + m * 2048 + k * 1024); } while (0)
; #define PG8_LDB(dst, b, h) do { _Pragma("unroll") for (int n = 0; n < 2; ++n) _Pragma("unroll") for (int k = 0; k < 2; ++k) dst[n][k] = *(const LAS bf16x8*)(lds + PG8_SB(b, h) + boff + n * 2048 + k * 1024); } while (0)
; #define PG8_MMA(ai, bj, At, Bt) do { __builtin_amdgcn_s_setprio(1); _Pragma("unroll") for (int m = 0; m < 4; ++m) _Pragma("unroll") for (int n = 0; n < 2; ++n) _Pragma("unroll") for (int k = 0; k < 2; ++k) \
;         acc[ai][bj][m][n] = __builtin_amdgcn_mfma_f32_16x16x32_bf16(Bt[n][k], At[m][k], acc[ai][bj][m][n], 0, 0, 0); __builtin_amdgcn_s_setprio(0); } while (0)
; #define PG8_WAIT_V(n) asm volatile("s_waitcnt vmcnt(" #n ")" ::: "memory")
; #define PG8_WAIT_L(n) asm volatile("s_waitcnt lgkmcnt(" #n ")" ::: "memory")
; #define PG8_BAR __builtin_amdgcn_s_barrier()
; #define PG8_SCHED __builtin_amdgcn_sched_barrier(0)
; __device__ __forceinline__ void gemm_phase(LAS unsigned char* lds, const Params& p, const Sched& S, float alpha, const int TIDX) {
;     ...
;             PG8_LDB(B0, 0, 0); PG8_SCHED; PG8_LDA(At, 0, 0); PG8_STAGE(PG8_SA(1, 1), a1 + hstep, voffA);
;             PG8_WAIT_L(8); PG8_BAR; PG8_WAIT_L(0); PG8_MMA(0, 0, At, B0); PG8_BAR; PG8_SCHED;
;             PG8_LDB(B1, 0, 1); PG8_STAGE(PG8_SB(0, 0), b2, voffB);
;             PG8_BAR; PG8_WAIT_L(0); PG8_MMA(0, 1, At, B1); PG8_BAR;
;     ...
;             PG8_BAR; PG8_WAIT_L(0); PG8_MMA(1, 0, At, B0); PG8_BAR; PG8_SCHED;
;             PG8_STAGE(PG8_SB(1, 1), b3 + hstep, voffB);
;             PG8_WAIT_V(6); PG8_BAR; PG8_MMA(1, 1, At, B1); PG8_BAR;
;         }
	s_waitcnt lgkmcnt(0)
	v_mfma_f32_16x16x32_bf16 v[62:65], v[130:133], v[162:165], v[62:65]
	v_mfma_f32_16x16x32_bf16 v[54:57], v[154:157], v[162:165], v[54:57]
	v_mfma_f32_16x16x32_bf16 v[46:49], v[130:133], v[174:177], v[46:49]
	v_mfma_f32_16x16x32_bf16 v[38:41], v[154:157], v[174:177], v[38:41]
	v_mfma_f32_16x16x32_bf16 v[30:33], v[130:133], v[182:185], v[30:33]
	v_mfma_f32_16x16x32_bf16 v[22:25], v[154:157], v[182:185], v[22:25]
	v_mfma_f32_16x16x32_bf16 v[14:17], v[130:133], v[208:211], v[14:17]
	v_mfma_f32_16x16x32_bf16 v[6:9], v[154:157], v[208:211], v[6:9]
	v_mfma_f32_16x16x32_bf16 v[62:65], v[134:137], v[170:173], v[62:65]
	v_mfma_f32_16x16x32_bf16 v[54:57], v[158:161], v[170:173], v[54:57]
	v_mfma_f32_16x16x32_bf16 v[46:49], v[134:137], v[178:181], v[46:49]
	v_mfma_f32_16x16x32_bf16 v[38:41], v[158:161], v[178:181], v[38:41]
	v_mfma_f32_16x16x32_bf16 v[30:33], v[134:137], v[204:207], v[30:33]
	v_mfma_f32_16x16x32_bf16 v[22:25], v[158:161], v[204:207], v[22:25]
	v_mfma_f32_16x16x32_bf16 v[14:17], v[134:137], v[212:215], v[14:17]
	v_mfma_f32_16x16x32_bf16 v[6:9], v[158:161], v[212:215], v[6:9]
	s_barrier
	s_add_i32 s48, s48, s34
	v_lshl_add_u64 v[130:131], v[236:237], 0, s[88:89]
	s_mov_b32 m0, s48
	s_nop 0
	global_load_lds_dwordx4 v[130:131], off
	v_lshl_add_u64 v[130:131], v[238:239], 0, s[88:89]
	s_add_i32 m0, s48, 0x2000
	s_nop 0
	global_load_lds_dwordx4 v[130:131], off
	s_waitcnt vmcnt(6)
	s_barrier
	v_mfma_f32_16x16x32_bf16 v[58:61], v[216:219], v[162:165], v[58:61]
	v_mfma_f32_16x16x32_bf16 v[50:53], v[224:227], v[162:165], v[50:53]
	v_mfma_f32_16x16x32_bf16 v[42:45], v[216:219], v[174:177], v[42:45]
	v_mfma_f32_16x16x32_bf16 v[34:37], v[224:227], v[174:177], v[34:37]
	v_mfma_f32_16x16x32_bf16 v[26:29], v[216:219], v[182:185], v[26:29]
	v_mfma_f32_16x16x32_bf16 v[18:21], v[224:227], v[182:185], v[18:21]
	v_mfma_f32_16x16x32_bf16 v[10:13], v[216:219], v[208:211], v[10:13]
	v_mfma_f32_16x16x32_bf16 v[2:5], v[224:227], v[208:211], v[2:5]
	v_mfma_f32_16x16x32_bf16 v[58:61], v[220:223], v[170:173], v[58:61]
	v_mfma_f32_16x16x32_bf16 v[50:53], v[228:231], v[170:173], v[50:53]
	v_mfma_f32_16x16x32_bf16 v[42:45], v[220:223], v[178:181], v[42:45]
	v_mfma_f32_16x16x32_bf16 v[34:37], v[228:231], v[178:181], v[34:37]
	v_mfma_f32_16x16x32_bf16 v[26:29], v[220:223], v[204:207], v[26:29]
	v_mfma_f32_16x16x32_bf16 v[18:21], v[228:231], v[204:207], v[18:21]
	v_mfma_f32_16x16x32_bf16 v[10:13], v[220:223], v[212:215], v[10:13]
	v_mfma_f32_16x16x32_bf16 v[2:5], v[228:231], v[212:215], v[2:5]
	s_add_u32 s6, s6, 0x100
	s_addc_u32 s7, s7, 0
	s_add_u32 s39, s39, 0x100
	s_addc_u32 s56, s56, 0
	s_cmp_ge_i32 s57, s79
	s_mov_b32 s48, s57
	s_barrier
	s_cbranch_scc0 .LBB0_289
	s_branch .LBB0_291
.LBB0_289:
	s_add_i32 s57, s48, 2
	s_add_u32 s50, s6, 0x80
	s_addc_u32 s49, s7, 0
	s_add_i32 s74, 0, 0x10000
	v_add_u32_e32 v0, s74, v200
	ds_read_b128 v[130:133], v0
	ds_read_b128 v[134:137], v0 offset:1024
	ds_read_b128 v[154:157], v0 offset:2048
	ds_read_b128 v[158:161], v0 offset:3072
	s_cmp_eq_u32 s38, s48
	s_cselect_b32 s48, s44, s50
	s_cselect_b32 s49, s45, s49
	s_cselect_b32 s51, s47, s56
	s_cselect_b32 s50, s46, s39
	v_lshl_add_u64 v[166:167], s[6:7], 0, v[150:151]
	s_add_i32 m0, s35, 0xc000
	ds_read_b128 v[162:165], v202
	ds_read_b128 v[170:173], v202 offset:1024
	ds_read_b128 v[174:177], v202 offset:2048
	ds_read_b128 v[178:181], v202 offset:3072
	ds_read_b128 v[182:185], v202 offset:4096
	ds_read_b128 v[204:207], v202 offset:5120
	ds_read_b128 v[208:211], v202 offset:6144
	ds_read_b128 v[212:215], v202 offset:7168
	global_load_lds_dwordx4 v[166:167], off
	v_lshl_add_u64 v[166:167], s[6:7], 0, v[152:153]
	s_add_i32 m0, s35, 0xe000
	s_nop 0
	global_load_lds_dwordx4 v[166:167], off
	s_waitcnt lgkmcnt(8)
	s_barrier
	s_waitcnt lgkmcnt(0)
	v_mfma_f32_16x16x32_bf16 v[126:129], v[130:133], v[162:165], v[126:129]
	v_mfma_f32_16x16x32_bf16 v[118:121], v[154:157], v[162:165], v[118:121]
	v_mfma_f32_16x16x32_bf16 v[110:113], v[130:133], v[174:177], v[110:113]
	v_mfma_f32_16x16x32_bf16 v[102:105], v[154:157], v[174:177], v[102:105]
	v_mfma_f32_16x16x32_bf16 v[94:97], v[130:133], v[182:185], v[94:97]
	v_mfma_f32_16x16x32_bf16 v[86:89], v[154:157], v[182:185], v[86:89]
	v_mfma_f32_16x16x32_bf16 v[78:81], v[130:133], v[208:211], v[78:81]
	v_mfma_f32_16x16x32_bf16 v[70:73], v[154:157], v[208:211], v[70:73]
	v_mfma_f32_16x16x32_bf16 v[126:129], v[134:137], v[170:173], v[126:129]
	v_mfma_f32_16x16x32_bf16 v[118:121], v[158:161], v[170:173], v[118:121]
	v_mfma_f32_16x16x32_bf16 v[110:113], v[134:137], v[178:181], v[110:113]
	v_mfma_f32_16x16x32_bf16 v[102:105], v[158:161], v[178:181], v[102:105]
	v_mfma_f32_16x16x32_bf16 v[94:97], v[134:137], v[204:207], v[94:97]
	v_mfma_f32_16x16x32_bf16 v[86:89], v[158:161], v[204:207], v[86:89]
	v_mfma_f32_16x16x32_bf16 v[78:81], v[134:137], v[212:215], v[78:81]
	v_mfma_f32_16x16x32_bf16 v[70:73], v[158:161], v[212:215], v[70:73]
	s_barrier
	s_add_i32 s75, 0, 0x14000
	s_add_i32 s74, s74, s34
	v_add_u32_e32 v0, s75, v200
	v_lshl_add_u64 v[166:167], s[50:51], 0, v[140:141]
	s_mov_b32 m0, s74
	ds_read_b128 v[216:219], v0
	ds_read_b128 v[220:223], v0 offset:1024
	ds_read_b128 v[224:227], v0 offset:2048
	ds_read_b128 v[228:231], v0 offset:3072
	global_load_lds_dwordx4 v[166:167], off
	v_lshl_add_u64 v[186:187], s[50:51], 0, v[144:145]
	s_add_i32 m0, s74, 0x2000
	s_nop 0
	global_load_lds_dwordx4 v[186:187], off
	s_barrier
; #define PG8_STAGE(bufoff, gbase, voff) do { _Pragma("unroll") for (int _i = 0; _i < 2; ++_i) \
;         __builtin_amdgcn_global_load_lds((const unsigned*)((const char*)(gbase) + (voff)[_i]), (LAS unsigned*)(lds + (bufoff) + ldsw + _i * 8192), 16, 0, 0); } while (0)
; #define PG8_LDA(dst, b, h) do { _Pragma("unroll") for (int m = 0; m < 4; ++m) _Pragma("unroll") for (int k = 0; k < 2; ++k) dst[m][k] = *(const LAS bf16x8*)(lds + PG8_SA(b, h) + aoff + m * 2048 + k * 1024); } while (0)
; #define PG8_LDB(dst, b, h) do { _Pragma("unroll") for (int n = 0; n < 2; ++n) _Pragma("unroll") for (int k = 0; k < 2; ++k) dst[n][k] = *(const LAS bf16x8*)(lds + PG8_SB(b, h) + boff + n * 2048 + k * 1024); } while (0)
; #define PG8_MMA(ai, bj, At, Bt) do { __builtin_amdgcn_s_setprio(1); _Pragma("unroll") for (int m = 0; m < 4; ++m) _Pragma("unroll") for (int n = 0; n < 2; ++n) _Pragma("unroll") for (int k = 0; k < 2; ++k) \
;         acc[ai][bj][m][n] = __builtin_amdgcn_mfma_f32_16x16x32_bf16(Bt[n][k], At[m][k], acc[ai][bj][m][n], 0, 0, 0); __builtin_amdgcn_s_setprio(0); } while (0)
; #define PG8_WAIT_V(n) asm volatile("s_waitcnt vmcnt(" #n ")" ::: "memory")
; #define PG8_WAIT_L(n) asm volatile("s_waitcnt lgkmcnt(" #n ")" ::: "memory")
; #define PG8_BAR __builtin_amdgcn_s_barrier()
; #define PG8_SCHED __builtin_amdgcn_sched_barrier(0)
; __device__ __forceinline__ void gemm_phase(LAS unsigned char* lds, const Params& p, const Sched& S, float alpha, const int TIDX) {
;     ...
;             PG8_BAR; PG8_WAIT_L(0); PG8_MMA(0, 1, At, B1); PG8_BAR;
;             PG8_LDA(At, 0, 1); PG8_STAGE(PG8_SA(0, 0), a2, voffA);
;             PG8_BAR; PG8_WAIT_L(0); PG8_MMA(1, 0, At, B0); PG8_BAR; PG8_SCHED;
;             PG8_STAGE(PG8_SB(0, 1), b2 + hstep, voffB);
;             PG8_WAIT_V(6); PG8_BAR; PG8_MMA(1, 1, At, B1); PG8_BAR;
;             PG8_LDB(B0, 1, 0); PG8_SCHED; PG8_LDA(At, 1, 0); PG8_STAGE(PG8_SA(0, 1), a2 + hstep, voffA);
;             PG8_WAIT_L(8); PG8_BAR; PG8_WAIT_L(0); PG8_MMA(0, 0, At, B0); PG8_BAR; PG8_SCHED;
;             PG8_LDB(B1, 1, 1); PG8_STAGE(PG8_SB(1, 0), b3, voffB);
	s_waitcnt lgkmcnt(0)
	v_mfma_f32_16x16x32_bf16 v[122:125], v[216:219], v[162:165], v[122:125]
	v_mfma_f32_16x16x32_bf16 v[114:117], v[224:227], v[162:165], v[114:117]
	v_mfma_f32_16x16x32_bf16 v[106:109], v[216:219], v[174:177], v[106:109]
	v_mfma_f32_16x16x32_bf16 v[98:101], v[224:227], v[174:177], v[98:101]
	v_mfma_f32_16x16x32_bf16 v[90:93], v[216:219], v[182:185], v[90:93]
	v_mfma_f32_16x16x32_bf16 v[82:85], v[224:227], v[182:185], v[82:85]
	v_mfma_f32_16x16x32_bf16 v[74:77], v[216:219], v[208:211], v[74:77]
	v_mfma_f32_16x16x32_bf16 v[66:69], v[224:227], v[208:211], v[66:69]
	v_mfma_f32_16x16x32_bf16 v[122:125], v[220:223], v[170:173], v[122:125]
	v_mfma_f32_16x16x32_bf16 v[114:117], v[228:231], v[170:173], v[114:117]
	v_mfma_f32_16x16x32_bf16 v[106:109], v[220:223], v[178:181], v[106:109]
	v_mfma_f32_16x16x32_bf16 v[98:101], v[228:231], v[178:181], v[98:101]
	v_mfma_f32_16x16x32_bf16 v[90:93], v[220:223], v[204:207], v[90:93]
	v_mfma_f32_16x16x32_bf16 v[82:85], v[228:231], v[204:207], v[82:85]
	v_mfma_f32_16x16x32_bf16 v[74:77], v[220:223], v[212:215], v[74:77]
	v_mfma_f32_16x16x32_bf16 v[66:69], v[228:231], v[212:215], v[66:69]
	s_mov_b32 m0, s35
	v_lshl_add_u64 v[232:233], s[48:49], 0, v[138:139]
	s_barrier
	ds_read_b128 v[162:165], v202 offset:16384
	ds_read_b128 v[170:173], v202 offset:17408
	ds_read_b128 v[174:177], v202 offset:18432
	ds_read_b128 v[178:181], v202 offset:19456
	ds_read_b128 v[182:185], v202 offset:20480
	ds_read_b128 v[204:207], v202 offset:21504
	ds_read_b128 v[208:211], v202 offset:22528
	ds_read_b128 v[212:215], v202 offset:23552
	global_load_lds_dwordx4 v[232:233], off
	v_lshl_add_u64 v[234:235], s[48:49], 0, v[142:143]
	s_mov_b32 m0, s36
	s_nop 0
	global_load_lds_dwordx4 v[234:235], off
	s_barrier
	s_waitcnt lgkmcnt(0)
	v_mfma_f32_16x16x32_bf16 v[62:65], v[130:133], v[162:165], v[62:65]
	v_mfma_f32_16x16x32_bf16 v[54:57], v[154:157], v[162:165], v[54:57]
	v_mfma_f32_16x16x32_bf16 v[46:49], v[130:133], v[174:177], v[46:49]
	v_mfma_f32_16x16x32_bf16 v[38:41], v[154:157], v[174:177], v[38:41]
	v_mfma_f32_16x16x32_bf16 v[30:33], v[130:133], v[182:185], v[30:33]
	v_mfma_f32_16x16x32_bf16 v[22:25], v[154:157], v[182:185], v[22:25]
	v_mfma_f32_16x16x32_bf16 v[14:17], v[130:133], v[208:211], v[14:17]
	v_mfma_f32_16x16x32_bf16 v[6:9], v[154:157], v[208:211], v[6:9]
	v_mfma_f32_16x16x32_bf16 v[62:65], v[134:137], v[170:173], v[62:65]
	v_mfma_f32_16x16x32_bf16 v[54:57], v[158:161], v[170:173], v[54:57]
	v_mfma_f32_16x16x32_bf16 v[46:49], v[134:137], v[178:181], v[46:49]
	v_mfma_f32_16x16x32_bf16 v[38:41], v[158:161], v[178:181], v[38:41]
	v_mfma_f32_16x16x32_bf16 v[30:33], v[134:137], v[204:207], v[30:33]
	v_mfma_f32_16x16x32_bf16 v[22:25], v[158:161], v[204:207], v[22:25]
	v_mfma_f32_16x16x32_bf16 v[14:17], v[134:137], v[212:215], v[14:17]
	v_mfma_f32_16x16x32_bf16 v[6:9], v[158:161], v[212:215], v[6:9]
	s_barrier
	s_add_u32 s50, s50, s20
	s_addc_u32 s51, s51, 0
	s_add_i32 s74, s75, s34
	v_lshl_add_u64 v[236:237], s[50:51], 0, v[140:141]
	s_mov_b32 m0, s74
	v_lshl_add_u64 v[238:239], s[50:51], 0, v[144:145]
	global_load_lds_dwordx4 v[236:237], off
	s_add_i32 m0, s74, 0x2000
	s_nop 0
	global_load_lds_dwordx4 v[238:239], off
	s_waitcnt vmcnt(6)
	s_barrier
	v_mfma_f32_16x16x32_bf16 v[58:61], v[216:219], v[162:165], v[58:61]
	v_mfma_f32_16x16x32_bf16 v[50:53], v[224:227], v[162:165], v[50:53]
	v_mfma_f32_16x16x32_bf16 v[42:45], v[216:219], v[174:177], v[42:45]
	v_mfma_f32_16x16x32_bf16 v[34:37], v[224:227], v[174:177], v[34:37]
	v_mfma_f32_16x16x32_bf16 v[26:29], v[216:219], v[182:185], v[26:29]
	v_mfma_f32_16x16x32_bf16 v[18:21], v[224:227], v[182:185], v[18:21]
	v_mfma_f32_16x16x32_bf16 v[10:13], v[216:219], v[208:211], v[10:13]
	v_mfma_f32_16x16x32_bf16 v[2:5], v[224:227], v[208:211], v[2:5]
	v_mfma_f32_16x16x32_bf16 v[58:61], v[220:223], v[170:173], v[58:61]
	v_mfma_f32_16x16x32_bf16 v[50:53], v[228:231], v[170:173], v[50:53]
	v_mfma_f32_16x16x32_bf16 v[42:45], v[220:223], v[178:181], v[42:45]
	v_mfma_f32_16x16x32_bf16 v[34:37], v[228:231], v[178:181], v[34:37]
	v_mfma_f32_16x16x32_bf16 v[26:29], v[220:223], v[204:207], v[26:29]
	v_mfma_f32_16x16x32_bf16 v[18:21], v[228:231], v[204:207], v[18:21]
	v_mfma_f32_16x16x32_bf16 v[10:13], v[220:223], v[212:215], v[10:13]
	v_mfma_f32_16x16x32_bf16 v[2:5], v[228:231], v[212:215], v[2:5]
	s_add_i32 s50, 0, 0x18000
	v_add_u32_e32 v0, s50, v200
	s_barrier
	ds_read_b128 v[130:133], v0
	ds_read_b128 v[134:137], v0 offset:1024
	ds_read_b128 v[154:157], v0 offset:2048
	ds_read_b128 v[158:161], v0 offset:3072
	s_add_u32 s48, s48, s20
	s_addc_u32 s49, s49, 0
	s_mov_b32 m0, s37
	v_lshl_add_u64 v[216:217], s[48:49], 0, v[138:139]
	ds_read_b128 v[162:165], v202 offset:32768
	ds_read_b128 v[170:173], v202 offset:33792
	ds_read_b128 v[174:177], v202 offset:34816
	ds_read_b128 v[178:181], v202 offset:35840
	ds_read_b128 v[182:185], v202 offset:36864
	ds_read_b128 v[204:207], v202 offset:37888
	ds_read_b128 v[208:211], v202 offset:38912
	ds_read_b128 v[212:215], v202 offset:39936
	global_load_lds_dwordx4 v[216:217], off
	v_lshl_add_u64 v[216:217], s[48:49], 0, v[142:143]
	s_mov_b32 m0, s24
	s_nop 0
	global_load_lds_dwordx4 v[216:217], off
	s_waitcnt lgkmcnt(8)
	s_barrier
; #define PG8_STAGE(bufoff, gbase, voff) do { _Pragma("unroll") for (int _i = 0; _i < 2; ++_i) \
;         __builtin_amdgcn_global_load_lds((const unsigned*)((const char*)(gbase) + (voff)[_i]), (LAS unsigned*)(lds + (bufoff) + ldsw + _i * 8192), 16, 0, 0); } while (0)
; #define PG8_LDA(dst, b, h) do { _Pragma("unroll") for (int m = 0; m < 4; ++m) _Pragma("unroll") for (int k = 0; k < 2; ++k) dst[m][k] = *(const LAS bf16x8*)(lds + PG8_SA(b, h) + aoff + m * 2048 + k * 1024); } while (0)
; #define PG8_LDB(dst, b, h) do { _Pragma("unroll") for (int n = 0; n < 2; ++n) _Pragma("unroll") for (int k = 0; k < 2; ++k) dst[n][k] = *(const LAS bf16x8*)(lds + PG8_SB(b, h) + boff + n * 2048 + k * 1024); } while (0)
; #define PG8_MMA(ai, bj, At, Bt) do { __builtin_amdgcn_s_setprio(1); _Pragma("unroll") for (int m = 0; m < 4; ++m) _Pragma("unroll") for (int n = 0; n < 2; ++n) _Pragma("unroll") for (int k = 0; k < 2; ++k) \
;         acc[ai][bj][m][n] = __builtin_amdgcn_mfma_f32_16x16x32_bf16(Bt[n][k], At[m][k], acc[ai][bj][m][n], 0, 0, 0); __builtin_amdgcn_s_setprio(0); } while (0)
; #define PG8_WAIT_V(n) asm volatile("s_waitcnt vmcnt(" #n ")" ::: "memory")
; #define PG8_WAIT_L(n) asm volatile("s_waitcnt lgkmcnt(" #n ")" ::: "memory")
; #define PG8_BAR __builtin_amdgcn_s_barrier()
; #define PG8_SCHED __builtin_amdgcn_sched_barrier(0)
; __device__ __forceinline__ void gemm_phase(LAS unsigned char* lds, const Params& p, const Sched& S, float alpha, const int TIDX) {
;     ...
;             PG8_WAIT_L(8); PG8_BAR; PG8_WAIT_L(0); PG8_MMA(0, 0, At, B0); PG8_BAR; PG8_SCHED;
;             PG8_LDB(B1, 1, 1); PG8_STAGE(PG8_SB(1, 0), b3, voffB);
;             PG8_BAR; PG8_WAIT_L(0); PG8_MMA(0, 1, At, B1); PG8_BAR;
;             PG8_LDA(At, 1, 1); PG8_STAGE(PG8_SA(1, 0), a3, voffA);
;             PG8_BAR; PG8_WAIT_L(0); PG8_MMA(1, 0, At, B0); PG8_BAR; PG8_SCHED;
;             PG8_STAGE(PG8_SB(1, 1), b3 + hstep, voffB);
;             PG8_WAIT_V(6); PG8_BAR; PG8_MMA(1, 1, At, B1); PG8_BAR;
;         }
	s_waitcnt lgkmcnt(0)
	v_mfma_f32_16x16x32_bf16 v[126:129], v[130:133], v[162:165], v[126:129]
	v_mfma_f32_16x16x32_bf16 v[118:121], v[154:157], v[162:165], v[118:121]
	v_mfma_f32_16x16x32_bf16 v[110:113], v[130:133], v[174:177], v[110:113]
	v_mfma_f32_16x16x32_bf16 v[102:105], v[154:157], v[174:177], v[102:105]
	v_mfma_f32_16x16x32_bf16 v[94:97], v[130:133], v[182:185], v[94:97]
	v_mfma_f32_16x16x32_bf16 v[86:89], v[154:157], v[182:185], v[86:89]
	v_mfma_f32_16x16x32_bf16 v[78:81], v[130:133], v[208:211], v[78:81]
	v_mfma_f32_16x16x32_bf16 v[70:73], v[154:157], v[208:211], v[70:73]
	v_mfma_f32_16x16x32_bf16 v[126:129], v[134:137], v[170:173], v[126:129]
	v_mfma_f32_16x16x32_bf16 v[118:121], v[158:161], v[170:173], v[118:121]
	v_mfma_f32_16x16x32_bf16 v[110:113], v[134:137], v[178:181], v[110:113]
	v_mfma_f32_16x16x32_bf16 v[102:105], v[158:161], v[178:181], v[102:105]
	v_mfma_f32_16x16x32_bf16 v[94:97], v[134:137], v[204:207], v[94:97]
	v_mfma_f32_16x16x32_bf16 v[86:89], v[158:161], v[204:207], v[86:89]
	v_mfma_f32_16x16x32_bf16 v[78:81], v[134:137], v[212:215], v[78:81]
	v_mfma_f32_16x16x32_bf16 v[70:73], v[158:161], v[212:215], v[70:73]
	s_barrier
	s_add_i32 s48, 0, 0x1c000
	s_add_i32 s49, s50, s34
	v_add_u32_e32 v0, s48, v200
	v_lshl_add_u64 v[166:167], v[166:167], 0, s[88:89]
	s_mov_b32 m0, s49
	ds_read_b128 v[216:219], v0
	ds_read_b128 v[220:223], v0 offset:1024
	ds_read_b128 v[224:227], v0 offset:2048
	ds_read_b128 v[228:231], v0 offset:3072
	global_load_lds_dwordx4 v[166:167], off
	v_lshl_add_u64 v[166:167], v[186:187], 0, s[88:89]
	s_add_i32 m0, s49, 0x2000
	s_nop 0
	global_load_lds_dwordx4 v[166:167], off
	s_barrier
	s_waitcnt lgkmcnt(0)
	v_mfma_f32_16x16x32_bf16 v[122:125], v[216:219], v[162:165], v[122:125]
	v_mfma_f32_16x16x32_bf16 v[114:117], v[224:227], v[162:165], v[114:117]
	v_mfma_f32_16x16x32_bf16 v[106:109], v[216:219], v[174:177], v[106:109]
	v_mfma_f32_16x16x32_bf16 v[98:101], v[224:227], v[174:177], v[98:101]
	v_mfma_f32_16x16x32_bf16 v[90:93], v[216:219], v[182:185], v[90:93]
	v_mfma_f32_16x16x32_bf16 v[82:85], v[224:227], v[182:185], v[82:85]
	v_mfma_f32_16x16x32_bf16 v[74:77], v[216:219], v[208:211], v[74:77]
	v_mfma_f32_16x16x32_bf16 v[66:69], v[224:227], v[208:211], v[66:69]
	v_mfma_f32_16x16x32_bf16 v[122:125], v[220:223], v[170:173], v[122:125]
	v_mfma_f32_16x16x32_bf16 v[114:117], v[228:231], v[170:173], v[114:117]
	v_mfma_f32_16x16x32_bf16 v[106:109], v[220:223], v[178:181], v[106:109]
	v_mfma_f32_16x16x32_bf16 v[98:101], v[228:231], v[178:181], v[98:101]
	v_mfma_f32_16x16x32_bf16 v[90:93], v[220:223], v[204:207], v[90:93]
	v_mfma_f32_16x16x32_bf16 v[82:85], v[228:231], v[204:207], v[82:85]
	v_mfma_f32_16x16x32_bf16 v[74:77], v[220:223], v[212:215], v[74:77]
	v_mfma_f32_16x16x32_bf16 v[66:69], v[228:231], v[212:215], v[66:69]
	s_mov_b32 m0, s25
	v_lshl_add_u64 v[166:167], v[232:233], 0, s[88:89]
	s_barrier
	ds_read_b128 v[162:165], v202 offset:49152
	ds_read_b128 v[170:173], v202 offset:50176
	ds_read_b128 v[174:177], v202 offset:51200
	ds_read_b128 v[178:181], v202 offset:52224
	ds_read_b128 v[182:185], v202 offset:53248
	ds_read_b128 v[204:207], v202 offset:54272
	ds_read_b128 v[208:211], v202 offset:55296
	ds_read_b128 v[212:215], v202 offset:56320
	global_load_lds_dwordx4 v[166:167], off
	v_lshl_add_u64 v[166:167], v[234:235], 0, s[88:89]
	s_mov_b32 m0, s68
	s_nop 0
	global_load_lds_dwordx4 v[166:167], off
	s_barrier
	s_waitcnt lgkmcnt(0)
	v_mfma_f32_16x16x32_bf16 v[62:65], v[130:133], v[162:165], v[62:65]
	v_mfma_f32_16x16x32_bf16 v[54:57], v[154:157], v[162:165], v[54:57]
	v_mfma_f32_16x16x32_bf16 v[46:49], v[130:133], v[174:177], v[46:49]
	v_mfma_f32_16x16x32_bf16 v[38:41], v[154:157], v[174:177], v[38:41]
	v_mfma_f32_16x16x32_bf16 v[30:33], v[130:133], v[182:185], v[30:33]
	v_mfma_f32_16x16x32_bf16 v[22:25], v[154:157], v[182:185], v[22:25]
	v_mfma_f32_16x16x32_bf16 v[14:17], v[130:133], v[208:211], v[14:17]
	v_mfma_f32_16x16x32_bf16 v[6:9], v[154:157], v[208:211], v[6:9]
	v_mfma_f32_16x16x32_bf16 v[62:65], v[134:137], v[170:173], v[62:65]
	v_mfma_f32_16x16x32_bf16 v[54:57], v[158:161], v[170:173], v[54:57]
	v_mfma_f32_16x16x32_bf16 v[46:49], v[134:137], v[178:181], v[46:49]
	v_mfma_f32_16x16x32_bf16 v[38:41], v[158:161], v[178:181], v[38:41]
	v_mfma_f32_16x16x32_bf16 v[30:33], v[134:137], v[204:207], v[30:33]
	v_mfma_f32_16x16x32_bf16 v[22:25], v[158:161], v[204:207], v[22:25]
	v_mfma_f32_16x16x32_bf16 v[14:17], v[134:137], v[212:215], v[14:17]
	v_mfma_f32_16x16x32_bf16 v[6:9], v[158:161], v[212:215], v[6:9]
	s_barrier
	s_add_i32 s48, s48, s34
	v_lshl_add_u64 v[130:131], v[236:237], 0, s[88:89]
	s_mov_b32 m0, s48
	s_nop 0
	global_load_lds_dwordx4 v[130:131], off
	v_lshl_add_u64 v[130:131], v[238:239], 0, s[88:89]
	s_add_i32 m0, s48, 0x2000
	s_nop 0
	global_load_lds_dwordx4 v[130:131], off
	s_waitcnt vmcnt(6)
	s_barrier
	v_mfma_f32_16x16x32_bf16 v[58:61], v[216:219], v[162:165], v[58:61]
	v_mfma_f32_16x16x32_bf16 v[50:53], v[224:227], v[162:165], v[50:53]
	v_mfma_f32_16x16x32_bf16 v[42:45], v[216:219], v[174:177], v[42:45]
	v_mfma_f32_16x16x32_bf16 v[34:37], v[224:227], v[174:177], v[34:37]
	v_mfma_f32_16x16x32_bf16 v[26:29], v[216:219], v[182:185], v[26:29]
	v_mfma_f32_16x16x32_bf16 v[18:21], v[224:227], v[182:185], v[18:21]
	v_mfma_f32_16x16x32_bf16 v[10:13], v[216:219], v[208:211], v[10:13]
	v_mfma_f32_16x16x32_bf16 v[2:5], v[224:227], v[208:211], v[2:5]
	v_mfma_f32_16x16x32_bf16 v[58:61], v[220:223], v[170:173], v[58:61]
	v_mfma_f32_16x16x32_bf16 v[50:53], v[228:231], v[170:173], v[50:53]
	v_mfma_f32_16x16x32_bf16 v[42:45], v[220:223], v[178:181], v[42:45]
	v_mfma_f32_16x16x32_bf16 v[34:37], v[228:231], v[178:181], v[34:37]
	v_mfma_f32_16x16x32_bf16 v[26:29], v[220:223], v[204:207], v[26:29]
	v_mfma_f32_16x16x32_bf16 v[18:21], v[228:231], v[204:207], v[18:21]
	v_mfma_f32_16x16x32_bf16 v[10:13], v[220:223], v[212:215], v[10:13]
	v_mfma_f32_16x16x32_bf16 v[2:5], v[228:231], v[212:215], v[2:5]
	s_add_u32 s6, s6, 0x100
	s_addc_u32 s7, s7, 0
	s_add_u32 s39, s39, 0x100
	s_addc_u32 s56, s56, 0
	s_cmp_ge_i32 s57, s79
	s_mov_b32 s48, s57
	s_barrier
	s_cbranch_scc0 .LBB0_289
	s_branch .LBB0_291
